# top-k unit outputs written through (sc1) in phases 6 and 14 so the barriers after them find a clean L2
# baseline (speedup 1.0000x reference)
.LBB0_730:
	s_or_b64 exec, exec, s[0:1]
	v_ashrrev_i32_e32 v3, 31, v2
	v_lshlrev_b64 v[2:3], 6, v[2:3]
	s_add_i32 s4, s4, s46
	v_lshl_add_u64 v[2:3], s[30:31], 0, v[2:3]
	s_cmp_gt_i32 s4, 63
	global_store_dword v[2:3], v4, off sc1
	s_cbranch_scc1 .LBB0_781

.LBB0_735:
	v_cmp_gt_u32_e32 vcc, v7, v34
	v_cmp_eq_u32_e64 s[24:25], v7, v34
	v_cmp_eq_u32_e64 s[30:31], v6, v34
	v_cndmask_b32_e64 v27, 0, 1, vcc
	v_cmp_gt_u32_e32 vcc, v6, v34
	v_cndmask_b32_e64 v33, 0, 1, s[24:25]
	v_cmp_eq_u32_e64 s[20:21], v8, v34
	v_addc_co_u32_e32 v27, vcc, 0, v27, vcc
	v_addc_co_u32_e64 v31, vcc, 0, v33, s[30:31]
	v_cmp_gt_u32_e32 vcc, v8, v34
	v_cndmask_b32_e64 v32, 0, 1, s[20:21]
	v_cmp_eq_u32_e64 s[16:17], v9, v34
	v_cndmask_b32_e64 v35, 0, 1, vcc
	v_cmp_gt_u32_e32 vcc, v9, v34
	v_cmp_eq_u32_e64 s[12:13], v2, v34
	v_cmp_eq_u32_e64 s[10:11], v3, v34
	v_addc_co_u32_e32 v27, vcc, v27, v35, vcc
	v_addc_co_u32_e64 v35, vcc, v31, v32, s[16:17]
	v_cmp_gt_u32_e32 vcc, v2, v34
	v_cndmask_b32_e64 v31, 0, 1, s[12:13]
	v_cmp_eq_u32_e64 s[6:7], v4, v34
	v_cndmask_b32_e64 v36, 0, 1, vcc
	v_cmp_gt_u32_e32 vcc, v3, v34
	v_cmp_lt_u32_e64 s[36:37], 31, v30
	v_cmp_le_u32_e64 s[34:35], v6, v34
	v_addc_co_u32_e32 v36, vcc, v27, v36, vcc
	v_addc_co_u32_e64 v35, vcc, v35, v31, s[10:11]
	v_cmp_gt_u32_e32 vcc, v4, v34
	v_cndmask_b32_e64 v27, 0, 1, s[6:7]
	v_cmp_le_u32_e64 s[28:29], v7, v34
	v_cndmask_b32_e64 v37, 0, 1, vcc
	v_cmp_gt_u32_e32 vcc, v5, v34
	v_cmp_le_u32_e64 s[26:27], v8, v34
	v_cmp_le_u32_e64 s[22:23], v9, v34
	v_addc_co_u32_e64 v36, s[0:1], v36, v37, vcc
	v_cmp_eq_u32_e64 s[0:1], v5, v34
	v_cmp_le_u32_e64 s[18:19], v2, v34
	s_nop 0
	v_addc_co_u32_e64 v35, s[14:15], v35, v27, s[0:1]
	v_cmp_lt_i32_e64 s[14:15], v21, v13
	v_lshl_or_b32 v35, v35, 16, v36
	s_barrier
	v_cndmask_b32_e64 v36, v21, v12, s[14:15]
	v_lshlrev_b32_e32 v36, 2, v36
	ds_bpermute_b32 v36, v36, v35
	v_cmp_le_u32_e64 s[14:15], v3, v34
	s_waitcnt lgkmcnt(0)
	v_cndmask_b32_e64 v36, v36, 0, s[8:9]
	v_cmp_lt_i32_e64 s[8:9], v22, v13
	v_add_u32_e32 v36, v36, v35
	s_nop 0
	v_cndmask_b32_e64 v37, v22, v12, s[8:9]
	v_lshlrev_b32_e32 v37, 2, v37
	ds_bpermute_b32 v37, v37, v36
	v_cmp_lt_u32_e64 s[8:9], 1, v30
	s_waitcnt lgkmcnt(0)
	s_nop 0
	v_cndmask_b32_e64 v37, 0, v37, s[8:9]
	v_cmp_lt_i32_e64 s[8:9], v23, v13
	v_add_u32_e32 v36, v37, v36
	s_nop 0
	v_cndmask_b32_e64 v37, v23, v12, s[8:9]
	v_lshlrev_b32_e32 v37, 2, v37
	ds_bpermute_b32 v37, v37, v36
	v_cmp_lt_u32_e64 s[8:9], 3, v30
	s_waitcnt lgkmcnt(0)
	s_nop 0
	v_cndmask_b32_e64 v37, 0, v37, s[8:9]
	v_cmp_lt_i32_e64 s[8:9], v24, v13
	v_add_u32_e32 v36, v37, v36
	s_nop 0
	v_cndmask_b32_e64 v37, v24, v12, s[8:9]
	v_lshlrev_b32_e32 v37, 2, v37
	ds_bpermute_b32 v37, v37, v36
	v_cmp_lt_u32_e64 s[8:9], 7, v30
	s_waitcnt lgkmcnt(0)
	s_nop 0
	v_cndmask_b32_e64 v37, 0, v37, s[8:9]
	v_cmp_lt_i32_e64 s[8:9], v25, v13
	v_add_u32_e32 v36, v37, v36
	s_nop 0
	v_cndmask_b32_e64 v37, v25, v12, s[8:9]
	v_lshlrev_b32_e32 v37, 2, v37
	ds_bpermute_b32 v37, v37, v36
	v_cmp_lt_u32_e64 s[8:9], 15, v30
	s_waitcnt lgkmcnt(0)
	s_nop 0
	v_cndmask_b32_e64 v37, 0, v37, s[8:9]
	v_cmp_lt_i32_e64 s[8:9], v26, v13
	v_add_u32_e32 v36, v37, v36
	s_nop 0
	v_cndmask_b32_e64 v37, v26, v12, s[8:9]
	v_lshlrev_b32_e32 v37, 2, v37
	ds_bpermute_b32 v37, v37, v36
	v_cmp_le_u32_e64 s[8:9], v4, v34
	s_waitcnt lgkmcnt(0)
	v_cndmask_b32_e64 v34, 0, v37, s[36:37]
	v_add_u32_e32 v34, v34, v36
	v_cmp_eq_u32_e64 s[36:37], 63, v30
	s_and_saveexec_b64 s[38:39], s[36:37]
	ds_write_b32 v29, v34 offset:16384
	s_or_b64 exec, exec, s[38:39]
	s_waitcnt lgkmcnt(0)
	s_barrier
	ds_read_b128 v[36:39], v1 offset:16384
	ds_read_b128 v[40:43], v1 offset:16400
	v_cmp_lt_i32_e64 s[36:37], 0, v28
	v_sub_u32_e32 v34, v34, v35
	s_movk_i32 s5, 0x200
	s_waitcnt lgkmcnt(1)
	v_cndmask_b32_e64 v29, 0, v36, s[36:37]
	v_cmp_lt_i32_e64 s[36:37], 1, v28
	v_add_u32_e32 v36, v37, v36
	v_add_u32_e32 v36, v36, v38
	v_cndmask_b32_e64 v30, 0, v37, s[36:37]
	v_cmp_lt_i32_e64 s[36:37], 2, v28
	v_add_u32_e32 v36, v36, v39
	s_waitcnt lgkmcnt(0)
	v_add_u32_e32 v36, v36, v40
	v_cndmask_b32_e64 v37, 0, v38, s[36:37]
	v_cmp_lt_i32_e64 s[36:37], 3, v28
	v_add3_u32 v29, v29, v34, v30
	v_add_u32_e32 v36, v36, v41
	v_cndmask_b32_e64 v38, 0, v39, s[36:37]
	v_cmp_lt_i32_e64 s[36:37], 4, v28
	v_add3_u32 v29, v29, v37, v38
	v_add_u32_e32 v36, v36, v42
	v_cndmask_b32_e64 v39, 0, v40, s[36:37]
	v_cmp_lt_i32_e64 s[36:37], 5, v28
	s_nop 1
	v_cndmask_b32_e64 v40, 0, v41, s[36:37]
	v_cmp_lt_i32_e64 s[36:37], 6, v28
	v_add3_u32 v29, v29, v39, v40
	s_nop 0
	v_cndmask_b32_e64 v41, 0, v42, s[36:37]
	v_cmp_lt_i32_e64 s[36:37], 7, v28
	v_add_u32_e32 v28, v36, v43
	v_sub_u32_sdwa v30, s5, v28 dst_sel:DWORD dst_unused:UNUSED_PAD src0_sel:DWORD src1_sel:WORD_0
	v_cndmask_b32_e64 v42, 0, v43, s[36:37]
	v_add3_u32 v34, v29, v41, v42
	v_lshrrev_b32_e32 v29, 16, v34
	s_and_saveexec_b64 s[36:37], s[34:35]
	s_xor_b64 s[36:37], exec, s[36:37]
	v_cmp_lt_u32_e64 s[34:35], v29, v30
	v_cndmask_b32_e64 v35, 0, 1, s[30:31]
	v_add_u32_sdwa v36, v29, v28 dst_sel:DWORD dst_unused:UNUSED_PAD src0_sel:DWORD src1_sel:WORD_0
	s_and_b64 s[30:31], s[30:31], s[34:35]
	v_add_u32_e32 v29, v29, v35
	v_cndmask_b32_e64 v35, -1, v36, s[30:31]
	s_or_saveexec_b64 s[30:31], s[36:37]
	v_and_b32_e32 v36, 0xffff, v34
	v_mov_b32_e32 v34, v36
	s_xor_b64 exec, exec, s[30:31]
	v_add_u32_e32 v34, 1, v36
	v_mov_b32_e32 v35, v36
	s_or_b64 exec, exec, s[30:31]
	s_lshl_b32 s5, s4, 9
	v_cmp_lt_i32_e64 s[30:31], -1, v35
	s_and_saveexec_b64 s[34:35], s[30:31]
	s_cbranch_execz .LBB0_743
	v_add_u32_e32 v36, s5, v35
	v_ashrrev_i32_e32 v37, 31, v36
	v_lshlrev_b64 v[36:37], 2, v[36:37]
	v_lshl_add_u64 v[38:39], s[50:51], 0, v[36:37]
	v_lshl_add_u64 v[36:37], s[52:53], 0, v[36:37]
	global_store_dword v[36:37], v10, off sc1
	global_store_dword v[38:39], v6, off sc1
.LBB0_743:
	s_or_b64 exec, exec, s[34:35]
	s_ashr_i32 s30, s4, 4
	s_ashr_i32 s31, s30, 31
	s_and_b32 s33, s4, 15
	s_lshl_b64 s[30:31], s[30:31], 18
	s_add_u32 s30, s54, s30
	s_addc_u32 s31, s55, s31
	s_lshl_b32 s33, s33, 2
	s_add_u32 s30, s30, s33
	s_addc_u32 s31, s31, 0
	v_lshlrev_b64 v[36:37], 6, v[10:11]
	v_lshl_add_u64 v[36:37], s[30:31], 0, v[36:37]
	global_store_dword v[36:37], v35, off sc1
	s_and_saveexec_b64 s[34:35], s[28:29]
	s_xor_b64 s[34:35], exec, s[34:35]
	v_cmp_lt_u32_e64 s[28:29], v29, v30
	v_add_u32_sdwa v6, v29, v28 dst_sel:DWORD dst_unused:UNUSED_PAD src0_sel:DWORD src1_sel:WORD_0
	s_and_b64 s[24:25], s[24:25], s[28:29]
	v_add_u32_e32 v29, v29, v33
	v_cndmask_b32_e64 v11, -1, v6, s[24:25]
	s_or_saveexec_b64 s[24:25], s[34:35]
	v_mov_b32_e32 v33, v34
	s_xor_b64 exec, exec, s[24:25]
	v_add_u32_e32 v33, 1, v34
	v_mov_b32_e32 v11, v34
	s_or_b64 exec, exec, s[24:25]
	v_or_b32_e32 v6, 1, v10
	v_cmp_lt_i32_e64 s[24:25], -1, v11
	s_and_saveexec_b64 s[28:29], s[24:25]
	s_cbranch_execz .LBB0_749
	v_add_u32_e32 v34, s5, v11
	v_ashrrev_i32_e32 v35, 31, v34
	v_lshlrev_b64 v[34:35], 2, v[34:35]
	v_lshl_add_u64 v[36:37], s[50:51], 0, v[34:35]
	v_lshl_add_u64 v[34:35], s[52:53], 0, v[34:35]
	global_store_dword v[34:35], v6, off sc1
	global_store_dword v[36:37], v7, off sc1
.LBB0_749:
	s_or_b64 exec, exec, s[28:29]
	v_ashrrev_i32_e32 v7, 31, v6
	v_lshlrev_b64 v[6:7], 6, v[6:7]
	v_lshl_add_u64 v[6:7], s[30:31], 0, v[6:7]
	global_store_dword v[6:7], v11, off sc1
	s_and_saveexec_b64 s[24:25], s[26:27]
	s_xor_b64 s[26:27], exec, s[24:25]
	v_cmp_lt_u32_e64 s[24:25], v29, v30
	v_add_u32_sdwa v6, v29, v28 dst_sel:DWORD dst_unused:UNUSED_PAD src0_sel:DWORD src1_sel:WORD_0
	s_and_b64 s[20:21], s[20:21], s[24:25]
	v_add_u32_e32 v29, v29, v32
	v_cndmask_b32_e64 v34, -1, v6, s[20:21]
	s_or_saveexec_b64 s[20:21], s[26:27]
	v_mov_b32_e32 v11, v33
	s_xor_b64 exec, exec, s[20:21]
	v_add_u32_e32 v11, 1, v33
	v_mov_b32_e32 v34, v33
	s_or_b64 exec, exec, s[20:21]
	v_or_b32_e32 v6, 2, v10
	v_cmp_lt_i32_e64 s[20:21], -1, v34
	s_and_saveexec_b64 s[24:25], s[20:21]
	s_cbranch_execz .LBB0_755
	v_add_u32_e32 v32, s5, v34
	v_ashrrev_i32_e32 v33, 31, v32
	v_lshlrev_b64 v[32:33], 2, v[32:33]
	v_lshl_add_u64 v[36:37], s[50:51], 0, v[32:33]
	v_lshl_add_u64 v[32:33], s[52:53], 0, v[32:33]
	global_store_dword v[32:33], v6, off sc1
	global_store_dword v[36:37], v8, off sc1
.LBB0_755:
	s_or_b64 exec, exec, s[24:25]
	v_ashrrev_i32_e32 v7, 31, v6
	v_lshlrev_b64 v[6:7], 6, v[6:7]
	v_lshl_add_u64 v[6:7], s[30:31], 0, v[6:7]
	global_store_dword v[6:7], v34, off sc1
	s_and_saveexec_b64 s[20:21], s[22:23]
	s_xor_b64 s[22:23], exec, s[20:21]
	v_cmp_lt_u32_e64 s[20:21], v29, v30
	v_cndmask_b32_e64 v6, 0, 1, s[16:17]
	v_add_u32_sdwa v7, v29, v28 dst_sel:DWORD dst_unused:UNUSED_PAD src0_sel:DWORD src1_sel:WORD_0
	s_and_b64 s[16:17], s[16:17], s[20:21]
	v_add_u32_e32 v29, v29, v6
	v_cndmask_b32_e64 v8, -1, v7, s[16:17]
	s_or_saveexec_b64 s[16:17], s[22:23]
	v_mov_b32_e32 v32, v11
	s_xor_b64 exec, exec, s[16:17]
	v_add_u32_e32 v32, 1, v11
	v_mov_b32_e32 v8, v11
	s_or_b64 exec, exec, s[16:17]
	v_or_b32_e32 v6, 3, v10
	v_cmp_lt_i32_e64 s[16:17], -1, v8
	s_and_saveexec_b64 s[20:21], s[16:17]
	s_cbranch_execz .LBB0_761
	v_add_u32_e32 v34, s5, v8
	v_ashrrev_i32_e32 v35, 31, v34
	v_lshlrev_b64 v[34:35], 2, v[34:35]
	v_lshl_add_u64 v[36:37], s[50:51], 0, v[34:35]
	v_lshl_add_u64 v[34:35], s[52:53], 0, v[34:35]
	global_store_dword v[34:35], v6, off sc1
	global_store_dword v[36:37], v9, off sc1
.LBB0_761:
	s_or_b64 exec, exec, s[20:21]
	v_ashrrev_i32_e32 v7, 31, v6
	v_lshlrev_b64 v[6:7], 6, v[6:7]
	v_lshl_add_u64 v[6:7], s[30:31], 0, v[6:7]
	global_store_dword v[6:7], v8, off sc1
	s_and_saveexec_b64 s[16:17], s[18:19]
	s_xor_b64 s[18:19], exec, s[16:17]
	v_cmp_lt_u32_e64 s[16:17], v29, v30
	v_add_u32_sdwa v6, v29, v28 dst_sel:DWORD dst_unused:UNUSED_PAD src0_sel:DWORD src1_sel:WORD_0
	s_and_b64 s[12:13], s[12:13], s[16:17]
	v_add_u32_e32 v29, v29, v31
	v_cndmask_b32_e64 v9, -1, v6, s[12:13]
	s_or_saveexec_b64 s[12:13], s[18:19]
	v_mov_b32_e32 v8, v32
	s_xor_b64 exec, exec, s[12:13]
	v_add_u32_e32 v8, 1, v32
	v_mov_b32_e32 v9, v32
	s_or_b64 exec, exec, s[12:13]
	v_or_b32_e32 v6, 4, v10
	v_cmp_lt_i32_e64 s[12:13], -1, v9
	s_and_saveexec_b64 s[16:17], s[12:13]
	s_cbranch_execz .LBB0_767
	v_add_u32_e32 v32, s5, v9
	v_ashrrev_i32_e32 v33, 31, v32
	v_lshlrev_b64 v[32:33], 2, v[32:33]
	v_lshl_add_u64 v[34:35], s[50:51], 0, v[32:33]
	v_lshl_add_u64 v[32:33], s[52:53], 0, v[32:33]
	global_store_dword v[32:33], v6, off sc1
	global_store_dword v[34:35], v2, off sc1
.LBB0_767:
	s_or_b64 exec, exec, s[16:17]
	v_ashrrev_i32_e32 v7, 31, v6
	v_lshlrev_b64 v[6:7], 6, v[6:7]
	v_lshl_add_u64 v[6:7], s[30:31], 0, v[6:7]
	global_store_dword v[6:7], v9, off sc1
	s_and_saveexec_b64 s[12:13], s[14:15]
	s_xor_b64 s[14:15], exec, s[12:13]
	v_cmp_lt_u32_e64 s[12:13], v29, v30
	v_cndmask_b32_e64 v2, 0, 1, s[10:11]
	v_add_u32_sdwa v6, v29, v28 dst_sel:DWORD dst_unused:UNUSED_PAD src0_sel:DWORD src1_sel:WORD_0
	s_and_b64 s[10:11], s[10:11], s[12:13]
	v_add_u32_e32 v29, v29, v2
	v_cndmask_b32_e64 v7, -1, v6, s[10:11]
	s_or_saveexec_b64 s[10:11], s[14:15]
	v_mov_b32_e32 v6, v8
	s_xor_b64 exec, exec, s[10:11]
	v_add_u32_e32 v6, 1, v8
	v_mov_b32_e32 v7, v8
	s_or_b64 exec, exec, s[10:11]
	v_or_b32_e32 v2, 5, v10
	v_cmp_lt_i32_e64 s[10:11], -1, v7
	s_and_saveexec_b64 s[12:13], s[10:11]
	s_cbranch_execz .LBB0_773
	v_add_u32_e32 v8, s5, v7
	v_ashrrev_i32_e32 v9, 31, v8
	v_lshlrev_b64 v[8:9], 2, v[8:9]
	v_lshl_add_u64 v[32:33], s[50:51], 0, v[8:9]
	v_lshl_add_u64 v[8:9], s[52:53], 0, v[8:9]
	global_store_dword v[8:9], v2, off sc1
	global_store_dword v[32:33], v3, off sc1
.LBB0_773:
	s_or_b64 exec, exec, s[12:13]
	v_ashrrev_i32_e32 v3, 31, v2
	v_lshlrev_b64 v[2:3], 6, v[2:3]
	v_lshl_add_u64 v[2:3], s[30:31], 0, v[2:3]
	global_store_dword v[2:3], v7, off sc1
	s_and_saveexec_b64 s[10:11], s[8:9]
	s_xor_b64 s[10:11], exec, s[10:11]
	v_cmp_lt_u32_e64 s[8:9], v29, v30
	v_add_u32_sdwa v2, v29, v28 dst_sel:DWORD dst_unused:UNUSED_PAD src0_sel:DWORD src1_sel:WORD_0
	s_and_b64 s[6:7], s[6:7], s[8:9]
	v_add_u32_e32 v29, v29, v27
	v_cndmask_b32_e64 v3, -1, v2, s[6:7]
	s_or_saveexec_b64 s[6:7], s[10:11]
	v_mov_b32_e32 v8, v6
	s_xor_b64 exec, exec, s[6:7]
	v_add_u32_e32 v8, 1, v6
	v_mov_b32_e32 v3, v6
	s_or_b64 exec, exec, s[6:7]
	v_or_b32_e32 v6, 6, v10
	v_cmp_lt_i32_e64 s[6:7], -1, v3
	s_and_saveexec_b64 s[8:9], s[6:7]
	s_cbranch_execz .LBB0_779
	v_add_u32_e32 v32, s5, v3
	v_ashrrev_i32_e32 v33, 31, v32
	v_lshlrev_b64 v[32:33], 2, v[32:33]
	v_lshl_add_u64 v[34:35], s[50:51], 0, v[32:33]
	v_lshl_add_u64 v[32:33], s[52:53], 0, v[32:33]
	global_store_dword v[32:33], v6, off sc1
	global_store_dword v[34:35], v4, off sc1
.LBB0_779:
	s_or_b64 exec, exec, s[8:9]
	v_ashrrev_i32_e32 v7, 31, v6
	v_lshlrev_b64 v[6:7], 6, v[6:7]
	v_lshl_add_u64 v[6:7], s[30:31], 0, v[6:7]
	v_cmp_lt_u32_e64 s[6:7], v29, v30
	global_store_dword v[6:7], v3, off sc1
	v_add_u32_sdwa v3, v29, v28 dst_sel:DWORD dst_unused:UNUSED_PAD src0_sel:DWORD src1_sel:WORD_0
	s_and_b64 s[0:1], s[0:1], s[6:7]
	v_cndmask_b32_e64 v3, -1, v3, s[0:1]
	v_cndmask_b32_e32 v4, v3, v8, vcc
	v_or_b32_e32 v2, 7, v10
	v_cmp_lt_i32_e32 vcc, -1, v4
	s_and_saveexec_b64 s[0:1], vcc
	s_cbranch_execz .LBB0_730
	v_add_u32_e32 v6, s5, v4
	v_ashrrev_i32_e32 v7, 31, v6
	v_lshlrev_b64 v[6:7], 2, v[6:7]
	v_lshl_add_u64 v[8:9], s[50:51], 0, v[6:7]
	v_lshl_add_u64 v[6:7], s[52:53], 0, v[6:7]
	global_store_dword v[6:7], v2, off sc1
	global_store_dword v[8:9], v5, off sc1
	s_branch .LBB0_730

.LBB0_1327:
	s_or_b64 exec, exec, s[0:1]
	v_ashrrev_i32_e32 v3, 31, v2
	v_lshlrev_b64 v[2:3], 6, v[2:3]
	s_add_i32 s2, s2, s46
	v_lshl_add_u64 v[2:3], s[4:5], 0, v[2:3]
	s_cmp_gt_i32 s2, 63
	global_store_dword v[2:3], v4, off sc1
	s_cbranch_scc1 .LBB0_1378

.LBB0_1332:
	v_cmp_gt_u32_e32 vcc, v7, v34
	v_cmp_eq_u32_e64 s[24:25], v7, v34
	v_cmp_eq_u32_e64 s[30:31], v6, v34
	v_cndmask_b32_e64 v27, 0, 1, vcc
	v_cmp_gt_u32_e32 vcc, v6, v34
	v_cndmask_b32_e64 v33, 0, 1, s[24:25]
	v_cmp_eq_u32_e64 s[20:21], v8, v34
	v_addc_co_u32_e32 v27, vcc, 0, v27, vcc
	v_addc_co_u32_e64 v31, vcc, 0, v33, s[30:31]
	v_cmp_gt_u32_e32 vcc, v8, v34
	v_cndmask_b32_e64 v32, 0, 1, s[20:21]
	v_cmp_eq_u32_e64 s[16:17], v9, v34
	v_cndmask_b32_e64 v35, 0, 1, vcc
	v_cmp_gt_u32_e32 vcc, v9, v34
	v_cmp_eq_u32_e64 s[12:13], v2, v34
	v_cmp_eq_u32_e64 s[10:11], v3, v34
	v_addc_co_u32_e32 v27, vcc, v27, v35, vcc
	v_addc_co_u32_e64 v35, vcc, v31, v32, s[16:17]
	v_cmp_gt_u32_e32 vcc, v2, v34
	v_cndmask_b32_e64 v31, 0, 1, s[12:13]
	v_cmp_eq_u32_e64 s[6:7], v4, v34
	v_cndmask_b32_e64 v36, 0, 1, vcc
	v_cmp_gt_u32_e32 vcc, v3, v34
	v_cmp_lt_u32_e64 s[36:37], 31, v30
	v_cmp_le_u32_e64 s[34:35], v6, v34
	v_addc_co_u32_e32 v36, vcc, v27, v36, vcc
	v_addc_co_u32_e64 v35, vcc, v35, v31, s[10:11]
	v_cmp_gt_u32_e32 vcc, v4, v34
	v_cndmask_b32_e64 v27, 0, 1, s[6:7]
	v_cmp_le_u32_e64 s[28:29], v7, v34
	v_cndmask_b32_e64 v37, 0, 1, vcc
	v_cmp_gt_u32_e32 vcc, v5, v34
	v_cmp_le_u32_e64 s[26:27], v8, v34
	v_cmp_le_u32_e64 s[22:23], v9, v34
	v_addc_co_u32_e64 v36, s[0:1], v36, v37, vcc
	v_cmp_eq_u32_e64 s[0:1], v5, v34
	v_cmp_le_u32_e64 s[18:19], v2, v34
	s_nop 0
	v_addc_co_u32_e64 v35, s[14:15], v35, v27, s[0:1]
	v_cmp_lt_i32_e64 s[14:15], v21, v13
	v_lshl_or_b32 v35, v35, 16, v36
	s_barrier
	v_cndmask_b32_e64 v36, v21, v12, s[14:15]
	v_lshlrev_b32_e32 v36, 2, v36
	ds_bpermute_b32 v36, v36, v35
	v_cmp_le_u32_e64 s[14:15], v3, v34
	s_waitcnt lgkmcnt(0)
	v_cndmask_b32_e64 v36, v36, 0, s[8:9]
	v_cmp_lt_i32_e64 s[8:9], v22, v13
	v_add_u32_e32 v36, v36, v35
	s_nop 0
	v_cndmask_b32_e64 v37, v22, v12, s[8:9]
	v_lshlrev_b32_e32 v37, 2, v37
	ds_bpermute_b32 v37, v37, v36
	v_cmp_lt_u32_e64 s[8:9], 1, v30
	s_waitcnt lgkmcnt(0)
	s_nop 0
	v_cndmask_b32_e64 v37, 0, v37, s[8:9]
	v_cmp_lt_i32_e64 s[8:9], v23, v13
	v_add_u32_e32 v36, v37, v36
	s_nop 0
	v_cndmask_b32_e64 v37, v23, v12, s[8:9]
	v_lshlrev_b32_e32 v37, 2, v37
	ds_bpermute_b32 v37, v37, v36
	v_cmp_lt_u32_e64 s[8:9], 3, v30
	s_waitcnt lgkmcnt(0)
	s_nop 0
	v_cndmask_b32_e64 v37, 0, v37, s[8:9]
	v_cmp_lt_i32_e64 s[8:9], v24, v13
	v_add_u32_e32 v36, v37, v36
	s_nop 0
	v_cndmask_b32_e64 v37, v24, v12, s[8:9]
	v_lshlrev_b32_e32 v37, 2, v37
	ds_bpermute_b32 v37, v37, v36
	v_cmp_lt_u32_e64 s[8:9], 7, v30
	s_waitcnt lgkmcnt(0)
	s_nop 0
	v_cndmask_b32_e64 v37, 0, v37, s[8:9]
	v_cmp_lt_i32_e64 s[8:9], v25, v13
	v_add_u32_e32 v36, v37, v36
	s_nop 0
	v_cndmask_b32_e64 v37, v25, v12, s[8:9]
	v_lshlrev_b32_e32 v37, 2, v37
	ds_bpermute_b32 v37, v37, v36
	v_cmp_lt_u32_e64 s[8:9], 15, v30
	s_waitcnt lgkmcnt(0)
	s_nop 0
	v_cndmask_b32_e64 v37, 0, v37, s[8:9]
	v_cmp_lt_i32_e64 s[8:9], v26, v13
	v_add_u32_e32 v36, v37, v36
	s_nop 0
	v_cndmask_b32_e64 v37, v26, v12, s[8:9]
	v_lshlrev_b32_e32 v37, 2, v37
	ds_bpermute_b32 v37, v37, v36
	v_cmp_le_u32_e64 s[8:9], v4, v34
	s_waitcnt lgkmcnt(0)
	v_cndmask_b32_e64 v34, 0, v37, s[36:37]
	v_add_u32_e32 v34, v34, v36
	v_cmp_eq_u32_e64 s[36:37], 63, v30
	s_and_saveexec_b64 s[4:5], s[36:37]
	ds_write_b32 v29, v34 offset:16384
	s_or_b64 exec, exec, s[4:5]
	s_waitcnt lgkmcnt(0)
	s_barrier
	ds_read_b128 v[36:39], v1 offset:16384
	ds_read_b128 v[40:43], v1 offset:16400
	v_cmp_lt_i32_e64 s[36:37], 0, v28
	v_sub_u32_e32 v34, v34, v35
	s_waitcnt lgkmcnt(1)
	v_cndmask_b32_e64 v29, 0, v36, s[36:37]
	v_cmp_lt_i32_e64 s[36:37], 1, v28
	v_add_u32_e32 v36, v37, v36
	v_add_u32_e32 v36, v36, v38
	v_cndmask_b32_e64 v30, 0, v37, s[36:37]
	v_cmp_lt_i32_e64 s[36:37], 2, v28
	v_add_u32_e32 v36, v36, v39
	s_waitcnt lgkmcnt(0)
	v_add_u32_e32 v36, v36, v40
	v_cndmask_b32_e64 v37, 0, v38, s[36:37]
	v_cmp_lt_i32_e64 s[36:37], 3, v28
	v_add3_u32 v29, v29, v34, v30
	v_add_u32_e32 v36, v36, v41
	v_cndmask_b32_e64 v38, 0, v39, s[36:37]
	v_cmp_lt_i32_e64 s[36:37], 4, v28
	v_add3_u32 v29, v29, v37, v38
	v_add_u32_e32 v36, v36, v42
	v_cndmask_b32_e64 v39, 0, v40, s[36:37]
	v_cmp_lt_i32_e64 s[36:37], 5, v28
	s_nop 1
	v_cndmask_b32_e64 v40, 0, v41, s[36:37]
	v_cmp_lt_i32_e64 s[36:37], 6, v28
	v_add3_u32 v29, v29, v39, v40
	s_nop 0
	v_cndmask_b32_e64 v41, 0, v42, s[36:37]
	v_cmp_lt_i32_e64 s[36:37], 7, v28
	v_add_u32_e32 v28, v36, v43
	v_sub_u32_sdwa v30, s38, v28 dst_sel:DWORD dst_unused:UNUSED_PAD src0_sel:DWORD src1_sel:WORD_0
	v_cndmask_b32_e64 v42, 0, v43, s[36:37]
	v_add3_u32 v34, v29, v41, v42
	v_lshrrev_b32_e32 v29, 16, v34
	s_and_saveexec_b64 s[4:5], s[34:35]
	s_xor_b64 s[4:5], exec, s[4:5]
	v_cmp_lt_u32_e64 s[34:35], v29, v30
	v_cndmask_b32_e64 v35, 0, 1, s[30:31]
	v_add_u32_sdwa v36, v29, v28 dst_sel:DWORD dst_unused:UNUSED_PAD src0_sel:DWORD src1_sel:WORD_0
	s_and_b64 s[30:31], s[30:31], s[34:35]
	v_add_u32_e32 v29, v29, v35
	v_cndmask_b32_e64 v35, -1, v36, s[30:31]
	s_or_saveexec_b64 s[4:5], s[4:5]
	v_and_b32_e32 v36, 0xffff, v34
	v_mov_b32_e32 v34, v36
	s_xor_b64 exec, exec, s[4:5]
	v_add_u32_e32 v34, 1, v36
	v_mov_b32_e32 v35, v36
	s_or_b64 exec, exec, s[4:5]
	s_lshl_b32 s3, s2, 9
	v_cmp_lt_i32_e64 s[30:31], -1, v35
	s_and_saveexec_b64 s[4:5], s[30:31]
	s_cbranch_execz .LBB0_1340
	v_add_u32_e32 v36, s3, v35
	v_ashrrev_i32_e32 v37, 31, v36
	v_lshlrev_b64 v[36:37], 2, v[36:37]
	v_lshl_add_u64 v[38:39], s[50:51], 0, v[36:37]
	v_lshl_add_u64 v[36:37], s[52:53], 0, v[36:37]
	global_store_dword v[36:37], v10, off sc1
	global_store_dword v[38:39], v6, off sc1
.LBB0_1340:
	s_or_b64 exec, exec, s[4:5]
	s_ashr_i32 s4, s2, 4
	s_ashr_i32 s5, s4, 31
	s_and_b32 s30, s2, 15
	s_lshl_b64 s[4:5], s[4:5], 18
	s_add_u32 s4, s54, s4
	s_addc_u32 s5, s55, s5
	s_lshl_b32 s30, s30, 2
	s_add_u32 s4, s4, s30
	s_addc_u32 s5, s5, 0
	v_lshlrev_b64 v[36:37], 6, v[10:11]
	v_lshl_add_u64 v[36:37], s[4:5], 0, v[36:37]
	global_store_dword v[36:37], v35, off sc1
	s_and_saveexec_b64 s[30:31], s[28:29]
	s_xor_b64 s[30:31], exec, s[30:31]
	v_cmp_lt_u32_e64 s[28:29], v29, v30
	v_add_u32_sdwa v6, v29, v28 dst_sel:DWORD dst_unused:UNUSED_PAD src0_sel:DWORD src1_sel:WORD_0
	s_and_b64 s[24:25], s[24:25], s[28:29]
	v_add_u32_e32 v29, v29, v33
	v_cndmask_b32_e64 v11, -1, v6, s[24:25]
	s_or_saveexec_b64 s[24:25], s[30:31]
	v_mov_b32_e32 v33, v34
	s_xor_b64 exec, exec, s[24:25]
	v_add_u32_e32 v33, 1, v34
	v_mov_b32_e32 v11, v34
	s_or_b64 exec, exec, s[24:25]
	v_or_b32_e32 v6, 1, v10
	v_cmp_lt_i32_e64 s[24:25], -1, v11
	s_and_saveexec_b64 s[28:29], s[24:25]
	s_cbranch_execz .LBB0_1346
	v_add_u32_e32 v34, s3, v11
	v_ashrrev_i32_e32 v35, 31, v34
	v_lshlrev_b64 v[34:35], 2, v[34:35]
	v_lshl_add_u64 v[36:37], s[50:51], 0, v[34:35]
	v_lshl_add_u64 v[34:35], s[52:53], 0, v[34:35]
	global_store_dword v[34:35], v6, off sc1
	global_store_dword v[36:37], v7, off sc1
.LBB0_1346:
	s_or_b64 exec, exec, s[28:29]
	v_ashrrev_i32_e32 v7, 31, v6
	v_lshlrev_b64 v[6:7], 6, v[6:7]
	v_lshl_add_u64 v[6:7], s[4:5], 0, v[6:7]
	global_store_dword v[6:7], v11, off sc1
	s_and_saveexec_b64 s[24:25], s[26:27]
	s_xor_b64 s[26:27], exec, s[24:25]
	v_cmp_lt_u32_e64 s[24:25], v29, v30
	v_add_u32_sdwa v6, v29, v28 dst_sel:DWORD dst_unused:UNUSED_PAD src0_sel:DWORD src1_sel:WORD_0
	s_and_b64 s[20:21], s[20:21], s[24:25]
	v_add_u32_e32 v29, v29, v32
	v_cndmask_b32_e64 v34, -1, v6, s[20:21]
	s_or_saveexec_b64 s[20:21], s[26:27]
	v_mov_b32_e32 v11, v33
	s_xor_b64 exec, exec, s[20:21]
	v_add_u32_e32 v11, 1, v33
	v_mov_b32_e32 v34, v33
	s_or_b64 exec, exec, s[20:21]
	v_or_b32_e32 v6, 2, v10
	v_cmp_lt_i32_e64 s[20:21], -1, v34
	s_and_saveexec_b64 s[24:25], s[20:21]
	s_cbranch_execz .LBB0_1352
	v_add_u32_e32 v32, s3, v34
	v_ashrrev_i32_e32 v33, 31, v32
	v_lshlrev_b64 v[32:33], 2, v[32:33]
	v_lshl_add_u64 v[36:37], s[50:51], 0, v[32:33]
	v_lshl_add_u64 v[32:33], s[52:53], 0, v[32:33]
	global_store_dword v[32:33], v6, off sc1
	global_store_dword v[36:37], v8, off sc1
.LBB0_1352:
	s_or_b64 exec, exec, s[24:25]
	v_ashrrev_i32_e32 v7, 31, v6
	v_lshlrev_b64 v[6:7], 6, v[6:7]
	v_lshl_add_u64 v[6:7], s[4:5], 0, v[6:7]
	global_store_dword v[6:7], v34, off sc1
	s_and_saveexec_b64 s[20:21], s[22:23]
	s_xor_b64 s[22:23], exec, s[20:21]
	v_cmp_lt_u32_e64 s[20:21], v29, v30
	v_cndmask_b32_e64 v6, 0, 1, s[16:17]
	v_add_u32_sdwa v7, v29, v28 dst_sel:DWORD dst_unused:UNUSED_PAD src0_sel:DWORD src1_sel:WORD_0
	s_and_b64 s[16:17], s[16:17], s[20:21]
	v_add_u32_e32 v29, v29, v6
	v_cndmask_b32_e64 v8, -1, v7, s[16:17]
	s_or_saveexec_b64 s[16:17], s[22:23]
	v_mov_b32_e32 v32, v11
	s_xor_b64 exec, exec, s[16:17]
	v_add_u32_e32 v32, 1, v11
	v_mov_b32_e32 v8, v11
	s_or_b64 exec, exec, s[16:17]
	v_or_b32_e32 v6, 3, v10
	v_cmp_lt_i32_e64 s[16:17], -1, v8
	s_and_saveexec_b64 s[20:21], s[16:17]
	s_cbranch_execz .LBB0_1358
	v_add_u32_e32 v34, s3, v8
	v_ashrrev_i32_e32 v35, 31, v34
	v_lshlrev_b64 v[34:35], 2, v[34:35]
	v_lshl_add_u64 v[36:37], s[50:51], 0, v[34:35]
	v_lshl_add_u64 v[34:35], s[52:53], 0, v[34:35]
	global_store_dword v[34:35], v6, off sc1
	global_store_dword v[36:37], v9, off sc1
.LBB0_1358:
	s_or_b64 exec, exec, s[20:21]
	v_ashrrev_i32_e32 v7, 31, v6
	v_lshlrev_b64 v[6:7], 6, v[6:7]
	v_lshl_add_u64 v[6:7], s[4:5], 0, v[6:7]
	global_store_dword v[6:7], v8, off sc1
	s_and_saveexec_b64 s[16:17], s[18:19]
	s_xor_b64 s[18:19], exec, s[16:17]
	v_cmp_lt_u32_e64 s[16:17], v29, v30
	v_add_u32_sdwa v6, v29, v28 dst_sel:DWORD dst_unused:UNUSED_PAD src0_sel:DWORD src1_sel:WORD_0
	s_and_b64 s[12:13], s[12:13], s[16:17]
	v_add_u32_e32 v29, v29, v31
	v_cndmask_b32_e64 v9, -1, v6, s[12:13]
	s_or_saveexec_b64 s[12:13], s[18:19]
	v_mov_b32_e32 v8, v32
	s_xor_b64 exec, exec, s[12:13]
	v_add_u32_e32 v8, 1, v32
	v_mov_b32_e32 v9, v32
	s_or_b64 exec, exec, s[12:13]
	v_or_b32_e32 v6, 4, v10
	v_cmp_lt_i32_e64 s[12:13], -1, v9
	s_and_saveexec_b64 s[16:17], s[12:13]
	s_cbranch_execz .LBB0_1364
	v_add_u32_e32 v32, s3, v9
	v_ashrrev_i32_e32 v33, 31, v32
	v_lshlrev_b64 v[32:33], 2, v[32:33]
	v_lshl_add_u64 v[34:35], s[50:51], 0, v[32:33]
	v_lshl_add_u64 v[32:33], s[52:53], 0, v[32:33]
	global_store_dword v[32:33], v6, off sc1
	global_store_dword v[34:35], v2, off sc1
.LBB0_1364:
	s_or_b64 exec, exec, s[16:17]
	v_ashrrev_i32_e32 v7, 31, v6
	v_lshlrev_b64 v[6:7], 6, v[6:7]
	v_lshl_add_u64 v[6:7], s[4:5], 0, v[6:7]
	global_store_dword v[6:7], v9, off sc1
	s_and_saveexec_b64 s[12:13], s[14:15]
	s_xor_b64 s[14:15], exec, s[12:13]
	v_cmp_lt_u32_e64 s[12:13], v29, v30
	v_cndmask_b32_e64 v2, 0, 1, s[10:11]
	v_add_u32_sdwa v6, v29, v28 dst_sel:DWORD dst_unused:UNUSED_PAD src0_sel:DWORD src1_sel:WORD_0
	s_and_b64 s[10:11], s[10:11], s[12:13]
	v_add_u32_e32 v29, v29, v2
	v_cndmask_b32_e64 v7, -1, v6, s[10:11]
	s_or_saveexec_b64 s[10:11], s[14:15]
	v_mov_b32_e32 v6, v8
	s_xor_b64 exec, exec, s[10:11]
	v_add_u32_e32 v6, 1, v8
	v_mov_b32_e32 v7, v8
	s_or_b64 exec, exec, s[10:11]
	v_or_b32_e32 v2, 5, v10
	v_cmp_lt_i32_e64 s[10:11], -1, v7
	s_and_saveexec_b64 s[12:13], s[10:11]
	s_cbranch_execz .LBB0_1370
	v_add_u32_e32 v8, s3, v7
	v_ashrrev_i32_e32 v9, 31, v8
	v_lshlrev_b64 v[8:9], 2, v[8:9]
	v_lshl_add_u64 v[32:33], s[50:51], 0, v[8:9]
	v_lshl_add_u64 v[8:9], s[52:53], 0, v[8:9]
	global_store_dword v[8:9], v2, off sc1
	global_store_dword v[32:33], v3, off sc1
.LBB0_1370:
	s_or_b64 exec, exec, s[12:13]
	v_ashrrev_i32_e32 v3, 31, v2
	v_lshlrev_b64 v[2:3], 6, v[2:3]
	v_lshl_add_u64 v[2:3], s[4:5], 0, v[2:3]
	global_store_dword v[2:3], v7, off sc1
	s_and_saveexec_b64 s[10:11], s[8:9]
	s_xor_b64 s[10:11], exec, s[10:11]
	v_cmp_lt_u32_e64 s[8:9], v29, v30
	v_add_u32_sdwa v2, v29, v28 dst_sel:DWORD dst_unused:UNUSED_PAD src0_sel:DWORD src1_sel:WORD_0
	s_and_b64 s[6:7], s[6:7], s[8:9]
	v_add_u32_e32 v29, v29, v27
	v_cndmask_b32_e64 v3, -1, v2, s[6:7]
	s_or_saveexec_b64 s[6:7], s[10:11]
	v_mov_b32_e32 v8, v6
	s_xor_b64 exec, exec, s[6:7]
	v_add_u32_e32 v8, 1, v6
	v_mov_b32_e32 v3, v6
	s_or_b64 exec, exec, s[6:7]
	v_or_b32_e32 v6, 6, v10
	v_cmp_lt_i32_e64 s[6:7], -1, v3
	s_and_saveexec_b64 s[8:9], s[6:7]
	s_cbranch_execz .LBB0_1376
	v_add_u32_e32 v32, s3, v3
	v_ashrrev_i32_e32 v33, 31, v32
	v_lshlrev_b64 v[32:33], 2, v[32:33]
	v_lshl_add_u64 v[34:35], s[50:51], 0, v[32:33]
	v_lshl_add_u64 v[32:33], s[52:53], 0, v[32:33]
	global_store_dword v[32:33], v6, off sc1
	global_store_dword v[34:35], v4, off sc1
.LBB0_1376:
	s_or_b64 exec, exec, s[8:9]
	v_ashrrev_i32_e32 v7, 31, v6
	v_lshlrev_b64 v[6:7], 6, v[6:7]
	v_lshl_add_u64 v[6:7], s[4:5], 0, v[6:7]
	v_cmp_lt_u32_e64 s[6:7], v29, v30
	global_store_dword v[6:7], v3, off sc1
	v_add_u32_sdwa v3, v29, v28 dst_sel:DWORD dst_unused:UNUSED_PAD src0_sel:DWORD src1_sel:WORD_0
	s_and_b64 s[0:1], s[0:1], s[6:7]
	v_cndmask_b32_e64 v3, -1, v3, s[0:1]
	v_cndmask_b32_e32 v4, v3, v8, vcc
	v_or_b32_e32 v2, 7, v10
	v_cmp_lt_i32_e32 vcc, -1, v4
	s_and_saveexec_b64 s[0:1], vcc
	s_cbranch_execz .LBB0_1327
	v_add_u32_e32 v6, s3, v4
	v_ashrrev_i32_e32 v7, 31, v6
	v_lshlrev_b64 v[6:7], 2, v[6:7]
	v_lshl_add_u64 v[8:9], s[50:51], 0, v[6:7]
	v_lshl_add_u64 v[6:7], s[52:53], 0, v[6:7]
	global_store_dword v[6:7], v2, off sc1
	global_store_dword v[8:9], v5, off sc1
	s_branch .LBB0_1327
